# gla_c: both state tiles S_f and S_b fetched once per workgroup as whole rows and staged through LDS regions that are dead at that point (one extra barrier); the S-section MFMA A fragments are LDS read
# speedup vs baseline: 1.0231x; 1.0110x over previous
.LBB0_828:
	s_or_b64 exec, exec, s[0:1]
	s_waitcnt lgkmcnt(1)
	v_lshl_add_u32 v56, v126, 2, 0
	v_add_u32_e32 v56, 0x10600, v56
	ds_write_b32 v56, v125
	s_waitcnt lgkmcnt(0)
	s_barrier
	ds_read_b32 v56, v88 offset:1024
	s_waitcnt lgkmcnt(0)
	v_cndmask_b32_e64 v57, 0, v56, s[8:9]
	v_cndmask_b32_e64 v58, 0, v56, s[10:11]
	v_cndmask_b32_e64 v57, v58, v57, s[4:5]
	v_add_f32_e32 v2, v2, v57
	v_add_f32_e32 v3, v3, v57
	v_add_f32_e32 v4, v4, v57
	v_add_f32_e32 v5, v5, v57
	v_add_f32_e32 v6, v6, v57
	v_add_f32_e32 v7, v7, v57
	v_add_f32_e32 v8, v8, v57
	v_add_f32_e32 v9, v9, v57
	v_add_f32_e32 v10, v10, v57
	v_add_f32_e32 v11, v11, v57
	v_add_f32_e32 v12, v12, v57
	v_add_f32_e32 v13, v13, v57
	ds_write2_b32 v49, v2, v3 offset0:2 offset1:131
	ds_write2_b32 v51, v4, v5 offset0:4 offset1:133
	ds_write2_b32 v53, v6, v7 offset0:6 offset1:135
	ds_write2_b32 v114, v8, v9 offset0:8 offset1:137
	ds_write2_b32 v117, v10, v11 offset0:10 offset1:139
	ds_write2_b32 v120, v12, v13 offset0:12 offset1:141
	v_add_f32_e32 v2, v0, v57
	v_add_f32_e32 v1, v1, v57
	v_add_f32_e32 v14, v14, v57
	v_add_f32_e32 v15, v15, v57
	v_add_f32_e32 v16, v16, v57
	v_add_f32_e32 v17, v17, v57
	v_add_f32_e32 v18, v18, v57
	v_add_f32_e32 v19, v19, v57
	v_add_f32_e32 v20, v20, v57
	v_add_f32_e32 v21, v21, v57
	v_add_f32_e32 v22, v22, v57
	ds_write2_b32 v112, v2, v1 offset1:129
	ds_write2_b32 v115, v14, v15 offset0:14 offset1:143
	ds_write2_b32 v118, v16, v17 offset0:16 offset1:145
	ds_write2_b32 v121, v18, v19 offset0:18 offset1:147
	ds_write2_b32 v123, v20, v21 offset0:20 offset1:149
	v_add_f32_e32 v1, v23, v57
	ds_write2_b32 v124, v22, v1 offset0:22 offset1:151
	v_add_f32_e32 v1, v24, v57
	v_add_f32_e32 v2, v25, v57
	ds_write2_b32 v122, v1, v2 offset0:24 offset1:153
	v_add_f32_e32 v1, v26, v57
	v_add_f32_e32 v2, v27, v57
	ds_write2_b32 v119, v1, v2 offset0:26 offset1:155
	v_add_f32_e32 v1, v28, v57
	v_add_f32_e32 v2, v29, v57
	ds_write2_b32 v116, v1, v2 offset0:28 offset1:157
	v_add_f32_e32 v1, v54, v57
	v_add_f32_e32 v2, v55, v57
	ds_write2_b32 v113, v1, v2 offset0:30 offset1:159
	s_and_saveexec_b64 s[0:1], s[10:11]
	v_cndmask_b32_e64 v0, v0, v56, s[4:5]
	v_cndmask_b32_e64 v1, v56, v55, s[4:5]
	v_add_f32_e32 v0, v0, v1
	ds_write_b32 v89, v0
	s_or_b64 exec, exec, s[0:1]
	v_or_b32_e32 v2, s44, v144
	v_mov_b64_e32 v[0:1], s[68:69]
	v_mad_i64_i32 v[0:1], s[0:1], v2, s79, v[0:1]
	s_lshl_b32 s70, s70, 1
	v_lshl_add_u64 v[0:1], v[0:1], 0, s[70:71]
	v_mov_b32_e32 v49, v31
	v_lshl_add_u64 v[16:17], v[0:1], 0, v[48:49]
	s_waitcnt vmcnt(0) lgkmcnt(0)
	s_barrier
	v_mov_b32_e32 v12, v150
	v_mov_b32_e32 v13, v151
	v_mov_b32_e32 v14, v152
	v_mov_b32_e32 v15, v153
	v_mov_b32_e32 v8, v154
	v_mov_b32_e32 v9, v155
	v_mov_b32_e32 v10, v156
	v_mov_b32_e32 v11, v157
	v_add_u32_e32 v0, 0x8100, v90
	v_add_u32_e32 v1, 0x8108, v90
	v_add_u32_e32 v2, 0x8110, v90
	ds_read2_b32 v[18:19], v90 offset1:1
	ds_read2_b32 v[20:21], v90 offset0:2 offset1:3
	ds_read2_b32 v[22:23], v90 offset0:4 offset1:5
	ds_read2_b32 v[24:25], v0 offset1:1
	ds_read2_b32 v[26:27], v1 offset1:1
	ds_read2_b32 v[28:29], v2 offset1:1
	v_mov_b32_e32 v4, v158
	v_mov_b32_e32 v5, v159
	v_mov_b32_e32 v6, v160
	v_mov_b32_e32 v7, v161
	v_mov_b32_e32 v0, v162
	v_mov_b32_e32 v1, v163
	v_mov_b32_e32 v2, v164
	v_mov_b32_e32 v3, v165
	s_lshl_b32 s98, s85, 3
	s_lshl_b32 s99, s86, 1
	s_or_b32 s98, s99, s98
	s_or_b32 s98, s98, 1
	s_ashr_i32 s99, s98, 31
	s_lshl_b64 s[98:99], s[98:99], 21
	s_add_u32 s98, s98, s52
	s_addc_u32 s99, s99, s53
	s_lshl_b32 s100, s45, 15
	s_add_u32 s98, s98, s100
	s_addc_u32 s99, s99, 0
	v_readlane_b32 s100, v244, 25
	v_lshrrev_b32_e32 v210, 4, v144
	v_and_b32_e32 v211, 15, v144
	v_lshl_add_u32 v210, s100, 4, v210
	v_lshlrev_b32_e32 v210, 8, v210
	v_lshl_add_u32 v210, v211, 4, v210
	global_load_dwordx4 v[150:153], v210, s[98:99]
	global_load_dwordx4 v[154:157], v210, s[98:99] offset:1024
	global_load_dwordx4 v[158:161], v210, s[98:99] offset:2048
	global_load_dwordx4 v[162:165], v210, s[98:99] offset:3072
	s_waitcnt lgkmcnt(5)
	v_mul_f32_e32 v49, 0x3fb8aa3b, v18
	v_mul_f32_e32 v51, 0xbfb8aa3b, v18
	v_mul_f32_e32 v53, 0x3fb8aa3b, v19
	v_mul_f32_e32 v54, 0xbfb8aa3b, v19
	s_waitcnt lgkmcnt(4)
	v_mul_f32_e32 v55, 0x3fb8aa3b, v20
	v_mul_f32_e32 v56, 0xbfb8aa3b, v20
	v_mul_f32_e32 v57, 0x3fb8aa3b, v21
	v_mul_f32_e32 v58, 0xbfb8aa3b, v21
	s_waitcnt lgkmcnt(3)
	v_mul_f32_e32 v59, 0x3fb8aa3b, v22
	v_mul_f32_e32 v60, 0xbfb8aa3b, v22
	v_mul_f32_e32 v61, 0x3fb8aa3b, v23
	v_mul_f32_e32 v62, 0xbfb8aa3b, v23
	s_waitcnt lgkmcnt(2)
	v_mul_f32_e32 v63, 0xbfb8aa3b, v25
	s_waitcnt lgkmcnt(1)
	v_mul_f32_e32 v64, 0x3fb8aa3b, v26
	v_mul_f32_e32 v65, 0xbfb8aa3b, v26
	v_mul_f32_e32 v66, 0x3fb8aa3b, v27
	v_mul_f32_e32 v67, 0xbfb8aa3b, v27
	v_exp_f32_e32 v18, v49
	v_exp_f32_e32 v20, v51
	v_mul_f32_e32 v49, 0x3fb8aa3b, v24
	v_mul_f32_e32 v51, 0xbfb8aa3b, v24
	v_exp_f32_e32 v19, v53
	v_exp_f32_e32 v21, v54
	v_mul_f32_e32 v53, 0x3fb8aa3b, v25
	v_exp_f32_e32 v22, v55
	v_exp_f32_e32 v24, v56
	v_exp_f32_e32 v23, v57
	v_exp_f32_e32 v25, v58
	v_exp_f32_e32 v26, v59
	v_exp_f32_e32 v54, v60
	v_exp_f32_e32 v27, v61
	v_exp_f32_e32 v55, v62
	v_exp_f32_e32 v59, v63
	v_exp_f32_e32 v60, v64
	v_exp_f32_e32 v62, v65
	v_exp_f32_e32 v61, v66
	v_exp_f32_e32 v63, v67
	s_waitcnt lgkmcnt(0)
	v_mul_f32_e32 v68, 0x3fb8aa3b, v28
	v_mul_f32_e32 v70, 0x3fb8aa3b, v29
	v_exp_f32_e32 v64, v68
	v_exp_f32_e32 v65, v70
	v_exp_f32_e32 v56, v49
	v_exp_f32_e32 v57, v53
	v_mul_f32_e32 v28, 0xbfb8aa3b, v28
	v_exp_f32_e32 v28, v28
	v_exp_f32_e32 v58, v51
	s_lshl_b32 s1, s86, 1
	s_lshl_b32 s45, s45, 15
	v_lshlrev_b32_e32 v66, 16, v12
	v_and_b32_e32 v67, 0xffff0000, v12
	v_lshlrev_b32_e32 v12, 16, v13
	v_and_b32_e32 v13, 0xffff0000, v13
	v_lshlrev_b32_e32 v68, 16, v8
	v_and_b32_e32 v69, 0xffff0000, v8
	v_lshlrev_b32_e32 v8, 16, v9
	v_and_b32_e32 v9, 0xffff0000, v9
	v_pk_mul_f32 v[66:67], v[66:67], s[74:75] op_sel_hi:[1,0]
	v_pk_mul_f32 v[12:13], v[12:13], s[74:75] op_sel_hi:[1,0]
	v_pk_mul_f32 v[62:63], v[62:63], v[8:9]
	v_pk_mul_f32 v[24:25], v[24:25], v[8:9]
	v_pk_mul_f32 v[8:9], v[66:67], v[18:19]
	v_pk_mul_f32 v[18:19], v[12:13], v[60:61]
	v_pk_mul_f32 v[12:13], v[12:13], v[22:23]
	v_lshlrev_b32_e32 v22, 16, v14
	v_and_b32_e32 v23, 0xffff0000, v14
	v_mul_f32_e32 v14, 0xbfb8aa3b, v29
	v_pk_mul_f32 v[22:23], v[22:23], s[74:75] op_sel_hi:[1,0]
	v_exp_f32_e32 v29, v14
	v_add_u32_e32 v14, 24, v90
	v_pk_mul_f32 v[60:61], v[22:23], v[64:65]
	v_pk_mul_f32 v[22:23], v[22:23], v[26:27]
	ds_read2st64_b32 v[26:27], v14 offset1:129
	v_pk_mul_f32 v[56:57], v[66:67], v[56:57]
	ds_read2st64_b32 v[66:67], v91 offset1:129
	v_lshlrev_b32_e32 v64, 16, v10
	v_and_b32_e32 v65, 0xffff0000, v10
	s_waitcnt lgkmcnt(1)
	v_mul_f32_e32 v10, 0x3fb8aa3b, v26
	v_pk_mul_f32 v[28:29], v[28:29], v[64:65]
	v_pk_mul_f32 v[54:55], v[54:55], v[64:65]
	v_exp_f32_e32 v64, v10
	v_mul_f32_e32 v10, 0xbfb8aa3b, v26
	v_exp_f32_e32 v26, v10
	v_mul_f32_e32 v10, 0x3fb8aa3b, v27
	v_pk_mul_f32 v[58:59], v[58:59], v[68:69]
	v_pk_mul_f32 v[20:21], v[20:21], v[68:69]
	v_exp_f32_e32 v68, v10
	v_mul_f32_e32 v10, 0xbfb8aa3b, v27
	v_exp_f32_e32 v14, v10
	s_waitcnt lgkmcnt(0)
	v_mul_f32_e32 v10, 0x3fb8aa3b, v66
	v_exp_f32_e32 v65, v10
	v_mul_f32_e32 v10, 0xbfb8aa3b, v66
	v_exp_f32_e32 v27, v10
	v_mul_f32_e32 v10, 0x3fb8aa3b, v67
	v_exp_f32_e32 v69, v10
	v_mul_f32_e32 v10, 0xbfb8aa3b, v67
	v_lshlrev_b32_e32 v70, 16, v15
	v_and_b32_e32 v71, 0xffff0000, v15
	v_exp_f32_e32 v15, v10
	v_pk_mul_f32 v[70:71], v[70:71], s[74:75] op_sel_hi:[1,0]
	v_lshlrev_b32_e32 v10, 16, v11
	v_pk_mul_f32 v[64:65], v[70:71], v[64:65]
	v_and_b32_e32 v11, 0xffff0000, v11
	v_pk_mul_f32 v[14:15], v[14:15], v[10:11]
	v_pk_mul_f32 v[26:27], v[26:27], v[10:11]
	v_cvt_pk_bf16_f32 v8, v8, v9
	v_cvt_pk_bf16_f32 v9, v12, v13
	v_cvt_pk_bf16_f32 v10, v22, v23
	v_cvt_pk_bf16_f32 v11, v64, v65
	v_pk_mul_f32 v[68:69], v[70:71], v[68:69]
	ds_write_b128 v92, v[8:11]
	v_cvt_pk_bf16_f32 v8, v20, v21
	v_cvt_pk_bf16_f32 v9, v24, v25
	v_cvt_pk_bf16_f32 v10, v54, v55
	v_cvt_pk_bf16_f32 v11, v26, v27
	ds_write_b128 v92, v[8:11] offset:17408
	v_cvt_pk_bf16_f32 v8, v56, v57
	v_cvt_pk_bf16_f32 v9, v18, v19
	v_cvt_pk_bf16_f32 v10, v60, v61
	v_cvt_pk_bf16_f32 v11, v68, v69
	ds_write_b128 v92, v[8:11] offset:34816
	v_cvt_pk_bf16_f32 v8, v58, v59
	v_cvt_pk_bf16_f32 v9, v62, v63
	v_cvt_pk_bf16_f32 v10, v28, v29
	v_cvt_pk_bf16_f32 v11, v14, v15
	ds_write_b128 v92, v[8:11] offset:52224
	ds_read2_b32 v[8:9], v90 offset0:64 offset1:65
	v_add_u32_e32 v10, 0x8200, v90
	ds_read2_b32 v[10:11], v10 offset1:1
	ds_read2_b32 v[12:13], v90 offset0:66 offset1:67
	ds_read2_b32 v[14:15], v90 offset0:68 offset1:69
	ds_read2_b32 v[18:19], v90 offset0:70 offset1:71
	v_add_u32_e32 v21, 0x8208, v90
	v_add_u32_e32 v24, 0x8210, v90
	v_add_u32_e32 v26, 0x8218, v90
	ds_read2_b32 v[22:23], v21 offset1:1
	ds_read2_b32 v[24:25], v24 offset1:1
	ds_read2_b32 v[26:27], v26 offset1:1
	s_waitcnt lgkmcnt(6)
	v_mul_f32_e32 v21, 0x3fb8aa3b, v10
	v_mul_f32_e32 v20, 0x3fb8aa3b, v8
	v_exp_f32_e32 v28, v21
	v_mul_f32_e32 v21, 0x3fb8aa3b, v9
	v_mul_f32_e32 v29, 0x3fb8aa3b, v11
	v_exp_f32_e32 v20, v20
	v_mul_f32_e32 v8, 0xbfb8aa3b, v8
	v_mul_f32_e32 v10, 0xbfb8aa3b, v10
	v_exp_f32_e32 v21, v21
	v_mul_f32_e32 v9, 0xbfb8aa3b, v9
	v_exp_f32_e32 v29, v29
	v_lshlrev_b32_e32 v54, 16, v4
	v_and_b32_e32 v55, 0xffff0000, v4
	v_mul_f32_e32 v4, 0xbfb8aa3b, v11
	v_exp_f32_e32 v8, v8
	v_exp_f32_e32 v10, v10
	v_exp_f32_e32 v9, v9
	v_exp_f32_e32 v11, v4
	v_pk_mul_f32 v[54:55], v[54:55], s[74:75] op_sel_hi:[1,0]
	v_lshlrev_b32_e32 v58, 16, v5
	v_pk_mul_f32 v[28:29], v[54:55], v[28:29]
	v_pk_mul_f32 v[20:21], v[54:55], v[20:21]
	v_lshlrev_b32_e32 v54, 16, v0
	v_and_b32_e32 v55, 0xffff0000, v0
	s_waitcnt lgkmcnt(5)
	v_mul_f32_e32 v0, 0x3fb8aa3b, v12
	v_pk_mul_f32 v[10:11], v[10:11], v[54:55]
	v_pk_mul_f32 v[8:9], v[8:9], v[54:55]
	v_exp_f32_e32 v54, v0
	v_mul_f32_e32 v0, 0xbfb8aa3b, v12
	v_exp_f32_e32 v12, v0
	s_waitcnt lgkmcnt(2)
	v_mul_f32_e32 v0, 0x3fb8aa3b, v22
	v_exp_f32_e32 v56, v0
	v_mul_f32_e32 v0, 0xbfb8aa3b, v22
	v_exp_f32_e32 v4, v0
	v_mul_f32_e32 v0, 0x3fb8aa3b, v13
	v_exp_f32_e32 v55, v0
	v_mul_f32_e32 v0, 0xbfb8aa3b, v13
	v_exp_f32_e32 v13, v0
	v_mul_f32_e32 v0, 0x3fb8aa3b, v23
	v_exp_f32_e32 v57, v0
	v_mul_f32_e32 v0, 0xbfb8aa3b, v23
	v_and_b32_e32 v59, 0xffff0000, v5
	v_exp_f32_e32 v5, v0
	v_lshlrev_b32_e32 v0, 16, v1
	v_and_b32_e32 v1, 0xffff0000, v1
	v_pk_mul_f32 v[12:13], v[12:13], v[0:1]
	v_pk_mul_f32 v[4:5], v[4:5], v[0:1]
	v_mul_f32_e32 v1, 0xbfb8aa3b, v14
	v_pk_mul_f32 v[58:59], v[58:59], s[74:75] op_sel_hi:[1,0]
	v_mul_f32_e32 v0, 0x3fb8aa3b, v14
	v_exp_f32_e32 v14, v1
	s_waitcnt lgkmcnt(1)
	v_mul_f32_e32 v1, 0x3fb8aa3b, v24
	v_pk_mul_f32 v[22:23], v[58:59], v[54:55]
	v_exp_f32_e32 v54, v1
	v_mul_f32_e32 v1, 0xbfb8aa3b, v24
	v_exp_f32_e32 v24, v1
	v_mul_f32_e32 v1, 0x3fb8aa3b, v15
	v_mul_f32_e32 v49, 0x3fb8aa3b, v25
	v_pk_mul_f32 v[56:57], v[58:59], v[56:57]
	v_exp_f32_e32 v0, v0
	v_exp_f32_e32 v1, v1
	v_mul_f32_e32 v15, 0xbfb8aa3b, v15
	v_exp_f32_e32 v55, v49
	v_lshlrev_b32_e32 v58, 16, v6
	v_and_b32_e32 v59, 0xffff0000, v6
	v_mul_f32_e32 v6, 0xbfb8aa3b, v25
	v_exp_f32_e32 v15, v15
	v_exp_f32_e32 v25, v6
	v_pk_mul_f32 v[58:59], v[58:59], s[74:75] op_sel_hi:[1,0]
	v_lshlrev_b32_e32 v62, 16, v7
	v_pk_mul_f32 v[54:55], v[58:59], v[54:55]
	v_pk_mul_f32 v[58:59], v[58:59], v[0:1]
	v_lshlrev_b32_e32 v0, 16, v2
	v_and_b32_e32 v1, 0xffff0000, v2
	v_pk_mul_f32 v[24:25], v[24:25], v[0:1]
	v_pk_mul_f32 v[14:15], v[14:15], v[0:1]
	v_mul_f32_e32 v1, 0xbfb8aa3b, v18
	v_mul_f32_e32 v0, 0x3fb8aa3b, v18
	v_exp_f32_e32 v18, v1
	s_waitcnt lgkmcnt(0)
	v_mul_f32_e32 v1, 0x3fb8aa3b, v26
	v_exp_f32_e32 v60, v1
	v_mul_f32_e32 v1, 0xbfb8aa3b, v26
	v_mul_f32_e32 v2, 0xbfb8aa3b, v19
	v_exp_f32_e32 v6, v1
	v_mul_f32_e32 v1, 0x3fb8aa3b, v19
	v_exp_f32_e32 v19, v2
	v_mul_f32_e32 v2, 0x3fb8aa3b, v27
	v_exp_f32_e32 v0, v0
	v_exp_f32_e32 v1, v1
	v_exp_f32_e32 v61, v2
	v_mul_f32_e32 v2, 0xbfb8aa3b, v27
	v_and_b32_e32 v63, 0xffff0000, v7
	v_exp_f32_e32 v7, v2
	v_pk_mul_f32 v[62:63], v[62:63], s[74:75] op_sel_hi:[1,0]
	v_cvt_pk_bf16_f32 v2, v58, v59
	v_pk_mul_f32 v[26:27], v[62:63], v[0:1]
	v_lshlrev_b32_e32 v0, 16, v3
	v_and_b32_e32 v1, 0xffff0000, v3
	v_pk_mul_f32 v[6:7], v[6:7], v[0:1]
	v_pk_mul_f32 v[18:19], v[18:19], v[0:1]
	v_cvt_pk_bf16_f32 v0, v20, v21
	v_cvt_pk_bf16_f32 v1, v22, v23
	v_cvt_pk_bf16_f32 v3, v26, v27
	v_pk_mul_f32 v[60:61], v[62:63], v[60:61]
	ds_write_b128 v92, v[0:3] offset:128
	v_cvt_pk_bf16_f32 v0, v8, v9
	v_cvt_pk_bf16_f32 v1, v12, v13
	v_cvt_pk_bf16_f32 v2, v14, v15
	v_cvt_pk_bf16_f32 v3, v18, v19
	ds_write_b128 v92, v[0:3] offset:17536
	v_cvt_pk_bf16_f32 v0, v28, v29
	v_cvt_pk_bf16_f32 v1, v56, v57
	v_cvt_pk_bf16_f32 v2, v54, v55
	v_cvt_pk_bf16_f32 v3, v60, v61
	ds_write_b128 v92, v[0:3] offset:34944
	v_cvt_pk_bf16_f32 v0, v10, v11
	v_cvt_pk_bf16_f32 v1, v4, v5
	v_cvt_pk_bf16_f32 v2, v24, v25
	v_cvt_pk_bf16_f32 v3, v6, v7
	ds_write_b128 v92, v[0:3] offset:52352
	s_waitcnt lgkmcnt(0)
	s_barrier
	v_mov_b32_e32 v0, v166
	v_mov_b32_e32 v1, v167
	v_mov_b32_e32 v2, v168
	v_mov_b32_e32 v3, v169
	v_mov_b32_e32 v4, v170
	v_mov_b32_e32 v5, v171
	v_mov_b32_e32 v6, v172
	v_mov_b32_e32 v7, v173
	v_readlane_b32 s99, v244, 25
	v_lshrrev_b32_e32 v210, 4, v144
	v_and_b32_e32 v211, 15, v144
	v_lshl_add_u32 v210, s99, 4, v210
	v_mul_u32_u24_e32 v210, 0x110, v210
	v_lshl_add_u32 v210, v211, 4, v210
	v_add_u32_e32 v186, 0x16c00, v210
	v_add_u32_e32 v210, 0x7000, v210
	ds_write_b128 v210, v[192:195]
	ds_write_b128 v210, v[196:199] offset:1088
	ds_write_b128 v210, v[232:235] offset:2176
	ds_write_b128 v210, v[236:239] offset:3264
	s_lshr_b32 s99, s99, 2
	s_mul_i32 s100, s99, 0x4400
	v_add_u32_e32 v186, s100, v186
	v_lshrrev_b32_e32 v211, 4, v144
	v_and_b32_e32 v210, 15, v144
	v_lshl_add_u32 v210, s99, 6, v210
	v_mul_u32_u24_e32 v210, 0x110, v210
	v_lshl_add_u32 v210, v211, 4, v210
	v_add_u32_e32 v211, 0x16c00, v210
	v_add_u32_e32 v211, s100, v211
	v_add_u32_e32 v210, 0x7000, v210
	ds_write_b16 v103, v0
	ds_write_b16_d16_hi v103, v0 offset:144
	ds_write_b16 v103, v1 offset:288
	ds_write_b16_d16_hi v103, v1 offset:432
	ds_write_b16 v103, v2 offset:576
	ds_write_b16_d16_hi v103, v2 offset:720
	ds_write_b16 v103, v3 offset:864
	ds_write_b16_d16_hi v104, v3
	ds_write_b16 v103, v4 offset:9216
	ds_write_b16_d16_hi v103, v4 offset:9360
	ds_write_b16 v103, v5 offset:9504
	ds_write_b16_d16_hi v103, v5 offset:9648
	ds_write_b16 v103, v6 offset:9792
	ds_write_b16_d16_hi v103, v6 offset:9936
	ds_write_b16 v103, v7 offset:10080
	ds_write_b16_d16_hi v103, v7 offset:10224
	ds_read_b128 v[0:3], v93
	ds_read_b128 v[4:7], v95 offset:17408
	ds_read_b128 v[8:11], v94
	ds_read_b128 v[12:15], v93 offset:64
	ds_read_b128 v[16:19], v95 offset:17472
	s_waitcnt lgkmcnt(3)
	v_mfma_f32_16x16x32_bf16 v[0:3], v[0:3], v[4:7], 0
	ds_read_b128 v[4:7], v95 offset:52224
	ds_read_b128 v[20:23], v94 offset:64
	ds_read_b128 v[24:27], v95 offset:52288
	s_waitcnt lgkmcnt(2)
	v_mfma_f32_16x16x32_bf16 v[4:7], v[8:11], v[4:7], 0
	v_mfma_f32_16x16x32_bf16 v[0:3], v[12:15], v[16:19], v[0:3]
	ds_read_b128 v[8:11], v93 offset:128
	ds_read_b128 v[12:15], v95 offset:17536
	s_waitcnt lgkmcnt(2)
	v_mfma_f32_16x16x32_bf16 v[4:7], v[20:23], v[24:27], v[4:7]
	ds_read_b128 v[16:19], v94 offset:128
	ds_read_b128 v[20:23], v93 offset:192
	ds_read_b128 v[24:27], v95 offset:17600
	s_waitcnt lgkmcnt(3)
	v_mfma_f32_16x16x32_bf16 v[0:3], v[8:11], v[12:15], v[0:3]
	ds_read_b128 v[8:11], v95 offset:52352
	ds_read_b128 v[12:15], v94 offset:192
	ds_read_b128 v[54:57], v95 offset:52416
	s_waitcnt lgkmcnt(2)
	v_mfma_f32_16x16x32_bf16 v[4:7], v[16:19], v[8:11], v[4:7]
	v_mfma_f32_16x16x32_bf16 v[0:3], v[20:23], v[24:27], v[0:3]
	s_waitcnt lgkmcnt(0)
	v_mfma_f32_16x16x32_bf16 v[4:7], v[12:15], v[54:57], v[4:7]
	s_nop 5
	v_cndmask_b32_e64 v0, v0, 0, s[12:13]
	s_nop 0
	v_cndmask_b32_e64 v4, v4, 0, s[14:15]
	v_add_f32_e32 v0, v0, v4
	v_cvt_pk_bf16_f32 v0, v0, s0
	ds_write_b16 v105, v0 offset:18432
	v_cndmask_b32_e64 v0, v1, 0, s[16:17]
	v_cndmask_b32_e64 v1, 0, v5, s[12:13]
	v_add_f32_e32 v0, v0, v1
	v_cvt_pk_bf16_f32 v0, v0, s0
	ds_write_b16 v105, v0 offset:18576
	v_cndmask_b32_e64 v0, v2, 0, s[18:19]
	v_cndmask_b32_e64 v1, v6, 0, s[20:21]
	v_add_f32_e32 v0, v0, v1
	v_cvt_pk_bf16_f32 v0, v0, s0
	ds_write_b16 v105, v0 offset:18720
	v_cndmask_b32_e64 v0, v3, 0, s[22:23]
	v_cndmask_b32_e64 v1, v7, 0, s[24:25]
	v_add_f32_e32 v0, v0, v1
	v_cvt_pk_bf16_f32 v0, v0, s0
	ds_write_b16 v105, v0 offset:18864
	ds_read_b128 v[0:3], v93
	ds_read_b128 v[4:7], v96 offset:17408
	ds_read_b128 v[8:11], v94
	ds_read_b128 v[12:15], v93 offset:64
	ds_read_b128 v[16:19], v96 offset:17472
	s_waitcnt lgkmcnt(3)
	v_mfma_f32_16x16x32_bf16 v[0:3], v[0:3], v[4:7], 0
	ds_read_b128 v[4:7], v96 offset:52224
	ds_read_b128 v[20:23], v94 offset:64
	ds_read_b128 v[24:27], v96 offset:52288
	s_waitcnt lgkmcnt(2)
	v_mfma_f32_16x16x32_bf16 v[4:7], v[8:11], v[4:7], 0
	v_mfma_f32_16x16x32_bf16 v[0:3], v[12:15], v[16:19], v[0:3]
	ds_read_b128 v[8:11], v93 offset:128
	ds_read_b128 v[12:15], v96 offset:17536
	s_waitcnt lgkmcnt(2)
	v_mfma_f32_16x16x32_bf16 v[4:7], v[20:23], v[24:27], v[4:7]
	ds_read_b128 v[16:19], v94 offset:128
	ds_read_b128 v[20:23], v93 offset:192
	ds_read_b128 v[24:27], v96 offset:17600
	s_waitcnt lgkmcnt(3)
	v_mfma_f32_16x16x32_bf16 v[0:3], v[8:11], v[12:15], v[0:3]
	ds_read_b128 v[8:11], v96 offset:52352
	ds_read_b128 v[12:15], v94 offset:192
	ds_read_b128 v[54:57], v96 offset:52416
	s_waitcnt lgkmcnt(2)
	v_mfma_f32_16x16x32_bf16 v[4:7], v[16:19], v[8:11], v[4:7]
	v_mfma_f32_16x16x32_bf16 v[0:3], v[20:23], v[24:27], v[0:3]
	s_waitcnt lgkmcnt(0)
	v_mfma_f32_16x16x32_bf16 v[4:7], v[12:15], v[54:57], v[4:7]
	s_nop 5
	v_cndmask_b32_e64 v0, v0, 0, s[26:27]
	s_nop 0
	v_cndmask_b32_e64 v4, v4, 0, s[28:29]
	v_add_f32_e32 v0, v0, v4
	v_cvt_pk_bf16_f32 v0, v0, s0
	ds_write_b16 v105, v0 offset:18464
	v_cndmask_b32_e64 v0, v1, 0, s[30:31]
	v_cndmask_b32_e64 v1, 0, v5, s[26:27]
	v_add_f32_e32 v0, v0, v1
	v_cvt_pk_bf16_f32 v0, v0, s0
	ds_write_b16 v105, v0 offset:18608
	v_cndmask_b32_e64 v0, v2, 0, s[34:35]
	v_cndmask_b32_e64 v1, v6, 0, s[36:37]
	v_add_f32_e32 v0, v0, v1
	v_cvt_pk_bf16_f32 v0, v0, s0
	ds_write_b16 v105, v0 offset:18752
	v_cndmask_b32_e64 v0, v3, 0, s[38:39]
	v_cndmask_b32_e64 v1, v7, 0, s[40:41]
	v_add_f32_e32 v0, v0, v1
	v_cvt_pk_bf16_f32 v0, v0, s0
	s_lshl_b32 s0, s85, 3
	s_or_b32 s0, s1, s0
	s_ashr_i32 s1, s0, 31
	s_lshl_b64 s[46:47], s[0:1], 21
	s_or_b32 s0, s0, 1
	s_ashr_i32 s1, s0, 31
	s_lshl_b64 s[0:1], s[0:1], 21
	s_add_u32 s48, s52, s0
	s_addc_u32 s49, s53, s1
	s_add_u32 s0, s52, s46
	s_addc_u32 s1, s53, s47
	s_add_u32 s0, s0, s45
	s_addc_u32 s1, s1, 0
	v_lshl_add_u64 v[28:29], s[0:1], 0, v[30:31]
	v_lshl_add_u64 v[24:25], v[28:29], 0, v[36:37]
	ds_write_b16 v105, v0 offset:18896
	s_waitcnt lgkmcnt(0)
	s_barrier
	s_waitcnt vmcnt(0)
	ds_write_b128 v186, v[150:153]
	ds_write_b128 v186, v[154:157] offset:1088
	ds_write_b128 v186, v[158:161] offset:2176
	ds_write_b128 v186, v[162:165] offset:3264
	ds_read_b128 v[16:19], v106 offset:18432
	ds_read_b128 v[20:23], v106 offset:18496
	ds_read_b128 v[58:61], v107
	ds_read_b128 v[74:77], v107 offset:64
	ds_read_b128 v[54:57], v98
	ds_read_b128 v[62:65], v98 offset:64
	ds_read_b128 v[66:69], v98 offset:128
	ds_read_b128 v[70:73], v98 offset:192
	ds_read_b128 v[194:197], v210
	ds_read_b128 v[198:201], v210 offset:64
	ds_read_b128 v[202:205], v210 offset:128
	ds_read_b128 v[206:209], v210 offset:192
	s_waitcnt lgkmcnt(9)
	v_mfma_f32_16x16x32_bf16 v[12:15], v[58:61], v[16:19], 0
	s_waitcnt lgkmcnt(8)
	v_mfma_f32_16x16x32_bf16 v[12:15], v[74:77], v[20:23], v[12:15]
	ds_read_b128 v[58:61], v107 offset:2304
	ds_read_b128 v[74:77], v107 offset:2368
	ds_read_b128 v[228:231], v210 offset:4352
	ds_read_b128 v[232:235], v210 offset:4416
	ds_read_b128 v[236:239], v210 offset:4480
	ds_read_b128 v[240:243], v210 offset:4544
	s_waitcnt lgkmcnt(13)
	s_waitcnt lgkmcnt(9)
	v_mfma_f32_16x16x32_bf16 v[12:15], v[194:197], v[54:57], v[12:15]
	s_waitcnt lgkmcnt(12)
	s_waitcnt lgkmcnt(8)
	v_mfma_f32_16x16x32_bf16 v[12:15], v[198:201], v[62:65], v[12:15]
	s_waitcnt lgkmcnt(11)
	s_waitcnt lgkmcnt(7)
	v_mfma_f32_16x16x32_bf16 v[12:15], v[202:205], v[66:69], v[12:15]
	s_waitcnt lgkmcnt(10)
	s_waitcnt lgkmcnt(6)
	v_mfma_f32_16x16x32_bf16 v[12:15], v[206:209], v[70:73], v[12:15]
	s_waitcnt lgkmcnt(5)
	v_mfma_f32_16x16x32_bf16 v[8:11], v[58:61], v[16:19], 0
	s_waitcnt lgkmcnt(4)
	v_mfma_f32_16x16x32_bf16 v[8:11], v[74:77], v[20:23], v[8:11]
	ds_read_b128 v[58:61], v107 offset:4608
	ds_read_b128 v[74:77], v107 offset:4672
	ds_read_b128 v[194:197], v210 offset:8704
	ds_read_b128 v[198:201], v210 offset:8768
	ds_read_b128 v[202:205], v210 offset:8832
	ds_read_b128 v[206:209], v210 offset:8896
	s_waitcnt lgkmcnt(9)
	v_mfma_f32_16x16x32_bf16 v[8:11], v[228:231], v[54:57], v[8:11]
	s_waitcnt lgkmcnt(8)
	v_mfma_f32_16x16x32_bf16 v[8:11], v[232:235], v[62:65], v[8:11]
	s_waitcnt lgkmcnt(7)
	v_mfma_f32_16x16x32_bf16 v[8:11], v[236:239], v[66:69], v[8:11]
	s_waitcnt lgkmcnt(6)
	v_mfma_f32_16x16x32_bf16 v[8:11], v[240:243], v[70:73], v[8:11]
	s_waitcnt lgkmcnt(5)
	v_mfma_f32_16x16x32_bf16 v[4:7], v[58:61], v[16:19], 0
	s_waitcnt lgkmcnt(4)
	v_mfma_f32_16x16x32_bf16 v[4:7], v[74:77], v[20:23], v[4:7]
	ds_read_b128 v[58:61], v108
	ds_read_b128 v[74:77], v108 offset:64
	ds_read_b128 v[228:231], v210 offset:13056
	ds_read_b128 v[232:235], v210 offset:13120
	ds_read_b128 v[236:239], v210 offset:13184
	ds_read_b128 v[240:243], v210 offset:13248
	s_waitcnt lgkmcnt(9)
	v_mfma_f32_16x16x32_bf16 v[4:7], v[194:197], v[54:57], v[4:7]
	s_waitcnt lgkmcnt(8)
	v_mfma_f32_16x16x32_bf16 v[4:7], v[198:201], v[62:65], v[4:7]
	s_waitcnt lgkmcnt(7)
	v_mfma_f32_16x16x32_bf16 v[4:7], v[202:205], v[66:69], v[4:7]
	s_waitcnt lgkmcnt(6)
	v_mfma_f32_16x16x32_bf16 v[4:7], v[206:209], v[70:73], v[4:7]
	s_waitcnt lgkmcnt(5)
	v_mfma_f32_16x16x32_bf16 v[0:3], v[58:61], v[16:19], 0
	s_waitcnt lgkmcnt(4)
	v_mfma_f32_16x16x32_bf16 v[0:3], v[74:77], v[20:23], v[0:3]
	ds_read_b128 v[24:27], v98 offset:34816
	ds_read_b128 v[78:81], v98 offset:34880
	ds_read_b128 v[114:117], v98 offset:34944
	ds_read_b128 v[118:121], v98 offset:35008
	s_waitcnt lgkmcnt(7)
	v_mfma_f32_16x16x32_bf16 v[0:3], v[228:231], v[54:57], v[0:3]
	s_waitcnt lgkmcnt(6)
	v_mfma_f32_16x16x32_bf16 v[0:3], v[232:235], v[62:65], v[0:3]
	s_waitcnt lgkmcnt(5)
	v_mfma_f32_16x16x32_bf16 v[0:3], v[236:239], v[66:69], v[0:3]
	s_waitcnt lgkmcnt(4)
	v_mfma_f32_16x16x32_bf16 v[0:3], v[240:243], v[70:73], v[0:3]
	s_waitcnt lgkmcnt(0)
	s_barrier
	ds_read_b128 v[194:197], v211
	ds_read_b128 v[198:201], v211 offset:64
	ds_read_b128 v[202:205], v211 offset:128
	ds_read_b128 v[206:209], v211 offset:192
	ds_read_b128 v[228:231], v211 offset:4352
	ds_read_b128 v[232:235], v211 offset:4416
	ds_read_b128 v[236:239], v211 offset:4480
	ds_read_b128 v[240:243], v211 offset:4544
	s_waitcnt lgkmcnt(7)
	v_mfma_f32_16x16x32_bf16 v[12:15], v[194:197], v[24:27], v[12:15]
	s_waitcnt lgkmcnt(6)
	v_mfma_f32_16x16x32_bf16 v[12:15], v[198:201], v[78:81], v[12:15]
	s_waitcnt lgkmcnt(5)
	v_mfma_f32_16x16x32_bf16 v[12:15], v[202:205], v[114:117], v[12:15]
	s_waitcnt lgkmcnt(4)
	v_mfma_f32_16x16x32_bf16 v[12:15], v[206:209], v[118:121], v[12:15]
	ds_read_b128 v[194:197], v211 offset:8704
	ds_read_b128 v[198:201], v211 offset:8768
	ds_read_b128 v[202:205], v211 offset:8832
	ds_read_b128 v[206:209], v211 offset:8896
	s_waitcnt lgkmcnt(7)
	v_mfma_f32_16x16x32_bf16 v[8:11], v[228:231], v[24:27], v[8:11]
	s_waitcnt lgkmcnt(6)
	v_mfma_f32_16x16x32_bf16 v[8:11], v[232:235], v[78:81], v[8:11]
	s_waitcnt lgkmcnt(5)
	v_mfma_f32_16x16x32_bf16 v[8:11], v[236:239], v[114:117], v[8:11]
	s_waitcnt lgkmcnt(4)
	v_mfma_f32_16x16x32_bf16 v[8:11], v[240:243], v[118:121], v[8:11]
	v_mul_f32_e32 v130, v13, v13
	v_mul_f32_e32 v131, v15, v15
	v_fmac_f32_e32 v130, v12, v12
	v_fmac_f32_e32 v131, v14, v14
	v_add_f32_e32 v130, v130, v131
	v_mov_b32_e32 v132, v130
	ds_read_b128 v[228:231], v211 offset:13056
	ds_read_b128 v[232:235], v211 offset:13120
	ds_read_b128 v[236:239], v211 offset:13184
	ds_read_b128 v[240:243], v211 offset:13248
	s_waitcnt lgkmcnt(7)
	v_mfma_f32_16x16x32_bf16 v[4:7], v[194:197], v[24:27], v[4:7]
	s_waitcnt lgkmcnt(6)
	v_mfma_f32_16x16x32_bf16 v[4:7], v[198:201], v[78:81], v[4:7]
	s_waitcnt lgkmcnt(5)
	v_mfma_f32_16x16x32_bf16 v[4:7], v[202:205], v[114:117], v[4:7]
	s_waitcnt lgkmcnt(4)
	v_mfma_f32_16x16x32_bf16 v[4:7], v[206:209], v[118:121], v[4:7]
	v_mul_f32_e32 v130, v9, v9
	v_mul_f32_e32 v131, v11, v11
	v_fmac_f32_e32 v130, v8, v8
	v_fmac_f32_e32 v131, v10, v10
	v_add_f32_e32 v130, v130, v131
	v_add_f32_e32 v132, v132, v130
	s_waitcnt lgkmcnt(3)
	v_mfma_f32_16x16x32_bf16 v[0:3], v[228:231], v[24:27], v[0:3]
	s_waitcnt lgkmcnt(2)
	v_mfma_f32_16x16x32_bf16 v[0:3], v[232:235], v[78:81], v[0:3]
	s_waitcnt lgkmcnt(1)
	v_mfma_f32_16x16x32_bf16 v[0:3], v[236:239], v[114:117], v[0:3]
	s_waitcnt lgkmcnt(0)
	v_mfma_f32_16x16x32_bf16 v[0:3], v[240:243], v[118:121], v[0:3]
	v_mul_f32_e32 v130, v5, v5
	v_mul_f32_e32 v131, v7, v7
	v_fmac_f32_e32 v130, v4, v4
	v_fmac_f32_e32 v131, v6, v6
	v_add_f32_e32 v130, v130, v131
	v_add_f32_e32 v132, v132, v130
	s_nop 7
	s_nop 1
	v_mul_f32_e32 v17, v1, v1
	v_mul_f32_e32 v18, v3, v3
	v_fmac_f32_e32 v17, v0, v0
	v_fmac_f32_e32 v18, v2, v2
	v_add_f32_e32 v17, v17, v18
	v_add_f32_e32 v16, v132, v17
	ds_bpermute_b32 v17, v101, v16
	s_waitcnt lgkmcnt(0)
	v_add_f32_e32 v16, v16, v17
	ds_bpermute_b32 v17, v102, v16
	s_and_saveexec_b64 s[0:1], s[42:43]
	s_cbranch_execz .LBB0_819
	s_waitcnt lgkmcnt(0)
	v_add_f32_e32 v16, v16, v17
	ds_write_b32 v99, v16 offset:27648
	s_branch .LBB0_819
